# v20a + FFN_UP k-loop: fused store-ladder/reload fast path for waves whose four ragged-row masks are full
# speedup vs baseline: 1.0065x; 1.0065x over previous
.LBB0_339:
	s_and_saveexec_b64 s[48:49], s[44:45]
	s_xor_b64 s[48:49], exec, s[48:49]
	s_cbranch_execz .LBB0_352
	s_cmp_gt_u32 s79, 13
	s_cbranch_scc1 .Lfu_0_old
	s_and_b64 s[90:91], s[88:89], s[22:23]
	s_and_b64 s[90:91], s[90:91], s[84:85]
	s_and_b64 s[90:91], s[90:91], s[86:87]
	s_cmp_eq_u64 s[90:91], -1
	s_cbranch_scc0 .Lfu_0_old
	s_andn2_b32 s40, 0x10000, s29
	v_add_u32_e32 v0, s40, v195
	s_waitcnt vmcnt(4)
	ds_write_b128 v0, v[144:147]
	v_lshl_add_u64 v[2:3], v[190:191], 0, s[20:21]
	global_load_dwordx4 v[144:147], v[2:3], off
	s_waitcnt vmcnt(4)
	ds_write_b128 v0, v[152:155] offset:32768
	v_lshl_add_u64 v[2:3], v[182:183], 0, s[20:21]
	global_load_dwordx4 v[152:155], v[2:3], off
	s_waitcnt vmcnt(5)
	ds_write_b128 v0, v[148:151] offset:8192
	v_lshl_add_u64 v[2:3], v[188:189], 0, s[20:21]
	global_load_dwordx4 v[148:151], v[2:3], off
	s_waitcnt vmcnt(5)
	ds_write_b128 v0, v[156:159] offset:40960
	v_lshl_add_u64 v[2:3], v[180:181], 0, s[20:21]
	global_load_dwordx4 v[156:159], v[2:3], off
	s_waitcnt vmcnt(6)
	ds_write_b128 v0, v[160:163] offset:16384
	v_lshl_add_u64 v[2:3], v[186:187], 0, s[20:21]
	global_load_dwordx4 v[160:163], v[2:3], off
	s_waitcnt vmcnt(6)
	ds_write_b128 v0, v[164:167] offset:49152
	v_lshl_add_u64 v[2:3], v[178:179], 0, s[20:21]
	global_load_dwordx4 v[164:167], v[2:3], off
	s_waitcnt vmcnt(7)
	ds_write_b128 v0, v[168:171] offset:24576
	v_lshl_add_u64 v[2:3], v[184:185], 0, s[20:21]
	global_load_dwordx4 v[168:171], v[2:3], off
	s_waitcnt vmcnt(7)
	ds_write_b128 v0, v[172:175] offset:57344
	v_lshl_add_u64 v[2:3], v[176:177], 0, s[20:21]
	global_load_dwordx4 v[172:175], v[2:3], off
	s_branch .Lfu_0_done
.Lfu_0_old:
	s_cmpk_eq_i32 s20, 0x780
	s_cbranch_scc1 .LBB0_342
	s_andn2_b32 s40, 0x10000, s29
	v_add_u32_e32 v0, s40, v195
	s_waitcnt vmcnt(4)
	ds_write_b128 v0, v[144:147]
	s_waitcnt vmcnt(3)
	ds_write_b128 v0, v[152:155] offset:32768
	ds_write_b128 v0, v[148:151] offset:8192
	s_waitcnt vmcnt(2)
	ds_write_b128 v0, v[156:159] offset:40960
	ds_write_b128 v0, v[160:163] offset:16384
	s_waitcnt vmcnt(1)
	ds_write_b128 v0, v[164:167] offset:49152
	ds_write_b128 v0, v[168:171] offset:24576
	s_waitcnt vmcnt(0)
	ds_write_b128 v0, v[172:175] offset:57344

.Lfu_0_done:
.LBB0_352:
	s_andn2_saveexec_b64 s[48:49], s[48:49]
	s_cbranch_execz .LBB0_354
	s_and_b32 s40, s29, 0x10000
	v_add_u32_e32 v0, s40, v198
	v_or_b32_e32 v2, s40, v199
	v_add_u32_e32 v14, v0, v201
	v_add_u32_e32 v15, v0, v202
	v_add_u32_e32 v205, v0, v203
	v_add_u32_e32 v0, v0, v204
	v_add_u32_e32 v248, v2, v201
	v_add_u32_e32 v249, v2, v202
	v_add_u32_e32 v250, v2, v203
	v_add_u32_e32 v251, v2, v204
	s_setprio 1
	ds_read_b128 v[2:5], v14 offset:0
	ds_read_b128 v[6:9], v14 offset:4096
	ds_read_b128 v[10:13], v14 offset:8192
	ds_read_b128 v[208:211], v14 offset:12288
	ds_read_b128 v[240:243], v248 offset:0
	ds_read_b128 v[244:247], v248 offset:4096
	ds_read_b128 v[214:217], v15 offset:0
	ds_read_b128 v[228:231], v15 offset:4096
	ds_read_b128 v[232:235], v15 offset:8192
	ds_read_b128 v[236:239], v15 offset:12288
	s_waitcnt lgkmcnt(4)
	v_mfma_f32_32x32x16_bf16 v[128:143], v[2:5], v[240:243], v[128:143]
	v_mfma_f32_32x32x16_bf16 v[96:111], v[6:9], v[240:243], v[96:111]
	v_mfma_f32_32x32x16_bf16 v[64:79], v[10:13], v[240:243], v[64:79]
	v_mfma_f32_32x32x16_bf16 v[32:47], v[208:211], v[240:243], v[32:47]
	ds_read_b128 v[240:243], v249 offset:0
	v_mfma_f32_32x32x16_bf16 v[112:127], v[2:5], v[244:247], v[112:127]
	v_mfma_f32_32x32x16_bf16 v[80:95], v[6:9], v[244:247], v[80:95]
	v_mfma_f32_32x32x16_bf16 v[48:63], v[10:13], v[244:247], v[48:63]
	v_mfma_f32_32x32x16_bf16 v[16:31], v[208:211], v[244:247], v[16:31]
	ds_read_b128 v[244:247], v249 offset:4096
	ds_read_b128 v[2:5], v205 offset:0
	ds_read_b128 v[6:9], v205 offset:4096
	ds_read_b128 v[10:13], v205 offset:8192
	ds_read_b128 v[208:211], v205 offset:12288
	s_waitcnt lgkmcnt(5)
	v_mfma_f32_32x32x16_bf16 v[128:143], v[214:217], v[240:243], v[128:143]
	v_mfma_f32_32x32x16_bf16 v[96:111], v[228:231], v[240:243], v[96:111]
	v_mfma_f32_32x32x16_bf16 v[64:79], v[232:235], v[240:243], v[64:79]
	v_mfma_f32_32x32x16_bf16 v[32:47], v[236:239], v[240:243], v[32:47]
	ds_read_b128 v[240:243], v250 offset:0
	s_waitcnt lgkmcnt(5)
	v_mfma_f32_32x32x16_bf16 v[112:127], v[214:217], v[244:247], v[112:127]
	v_mfma_f32_32x32x16_bf16 v[80:95], v[228:231], v[244:247], v[80:95]
	v_mfma_f32_32x32x16_bf16 v[48:63], v[232:235], v[244:247], v[48:63]
	v_mfma_f32_32x32x16_bf16 v[16:31], v[236:239], v[244:247], v[16:31]
	ds_read_b128 v[244:247], v250 offset:4096
	ds_read_b128 v[214:217], v0 offset:0
	ds_read_b128 v[228:231], v0 offset:4096
	ds_read_b128 v[232:235], v0 offset:8192
	ds_read_b128 v[236:239], v0 offset:12288
	s_waitcnt lgkmcnt(5)
	v_mfma_f32_32x32x16_bf16 v[128:143], v[2:5], v[240:243], v[128:143]
	v_mfma_f32_32x32x16_bf16 v[96:111], v[6:9], v[240:243], v[96:111]
	v_mfma_f32_32x32x16_bf16 v[64:79], v[10:13], v[240:243], v[64:79]
	v_mfma_f32_32x32x16_bf16 v[32:47], v[208:211], v[240:243], v[32:47]
	ds_read_b128 v[240:243], v251 offset:0
	s_waitcnt lgkmcnt(5)
	v_mfma_f32_32x32x16_bf16 v[112:127], v[2:5], v[244:247], v[112:127]
	v_mfma_f32_32x32x16_bf16 v[80:95], v[6:9], v[244:247], v[80:95]
	v_mfma_f32_32x32x16_bf16 v[48:63], v[10:13], v[244:247], v[48:63]
	v_mfma_f32_32x32x16_bf16 v[16:31], v[208:211], v[244:247], v[16:31]
	ds_read_b128 v[244:247], v251 offset:4096
	s_waitcnt lgkmcnt(1)
	v_mfma_f32_32x32x16_bf16 v[128:143], v[214:217], v[240:243], v[128:143]
	v_mfma_f32_32x32x16_bf16 v[96:111], v[228:231], v[240:243], v[96:111]
	v_mfma_f32_32x32x16_bf16 v[64:79], v[232:235], v[240:243], v[64:79]
	v_mfma_f32_32x32x16_bf16 v[32:47], v[236:239], v[240:243], v[32:47]
	s_waitcnt lgkmcnt(0)
	v_mfma_f32_32x32x16_bf16 v[112:127], v[214:217], v[244:247], v[112:127]
	v_mfma_f32_32x32x16_bf16 v[80:95], v[228:231], v[244:247], v[80:95]
	v_mfma_f32_32x32x16_bf16 v[48:63], v[232:235], v[244:247], v[48:63]
	v_mfma_f32_32x32x16_bf16 v[16:31], v[236:239], v[244:247], v[16:31]
	s_nop 15
	s_nop 7

	s_setprio 0
.LBB0_354:
	s_or_b64 exec, exec, s[48:49]
	s_and_saveexec_b64 s[40:41], s[46:47]
	s_xor_b64 s[48:49], exec, s[40:41]
	s_cbranch_execz .LBB0_367
	s_cmp_gt_u32 s79, 13
	s_cbranch_scc1 .Lfu_1_old
	s_and_b64 s[90:91], s[88:89], s[22:23]
	s_and_b64 s[90:91], s[90:91], s[84:85]
	s_and_b64 s[90:91], s[90:91], s[86:87]
	s_cmp_eq_u64 s[90:91], -1
	s_cbranch_scc0 .Lfu_1_old
	s_andn2_b32 s40, 0x10000, s29
	v_add_u32_e32 v0, s40, v195
	s_waitcnt vmcnt(4)
	ds_write_b128 v0, v[144:147]
	v_lshl_add_u64 v[2:3], v[190:191], 0, s[20:21]
	global_load_dwordx4 v[144:147], v[2:3], off
	s_waitcnt vmcnt(4)
	ds_write_b128 v0, v[152:155] offset:32768
	v_lshl_add_u64 v[2:3], v[182:183], 0, s[20:21]
	global_load_dwordx4 v[152:155], v[2:3], off
	s_waitcnt vmcnt(5)
	ds_write_b128 v0, v[148:151] offset:8192
	v_lshl_add_u64 v[2:3], v[188:189], 0, s[20:21]
	global_load_dwordx4 v[148:151], v[2:3], off
	s_waitcnt vmcnt(5)
	ds_write_b128 v0, v[156:159] offset:40960
	v_lshl_add_u64 v[2:3], v[180:181], 0, s[20:21]
	global_load_dwordx4 v[156:159], v[2:3], off
	s_waitcnt vmcnt(6)
	ds_write_b128 v0, v[160:163] offset:16384
	v_lshl_add_u64 v[2:3], v[186:187], 0, s[20:21]
	global_load_dwordx4 v[160:163], v[2:3], off
	s_waitcnt vmcnt(6)
	ds_write_b128 v0, v[164:167] offset:49152
	v_lshl_add_u64 v[2:3], v[178:179], 0, s[20:21]
	global_load_dwordx4 v[164:167], v[2:3], off
	s_waitcnt vmcnt(7)
	ds_write_b128 v0, v[168:171] offset:24576
	v_lshl_add_u64 v[2:3], v[184:185], 0, s[20:21]
	global_load_dwordx4 v[168:171], v[2:3], off
	s_waitcnt vmcnt(7)
	ds_write_b128 v0, v[172:175] offset:57344
	v_lshl_add_u64 v[2:3], v[176:177], 0, s[20:21]
	global_load_dwordx4 v[172:175], v[2:3], off
	s_branch .Lfu_1_done

.Lfu_1_done:
.LBB0_367:
	s_andn2_saveexec_b64 s[48:49], s[48:49]
	s_cbranch_execz .LBB0_338
	s_and_b32 s40, s29, 0x10000
	v_add_u32_e32 v0, s40, v198
	v_or_b32_e32 v2, s40, v199
	v_add_u32_e32 v14, v0, v201
	v_add_u32_e32 v15, v0, v202
	v_add_u32_e32 v205, v0, v203
	v_add_u32_e32 v0, v0, v204
	v_add_u32_e32 v248, v2, v201
	v_add_u32_e32 v249, v2, v202
	v_add_u32_e32 v250, v2, v203
	v_add_u32_e32 v251, v2, v204
	s_setprio 1
	ds_read_b128 v[2:5], v14 offset:0
	ds_read_b128 v[6:9], v14 offset:4096
	ds_read_b128 v[10:13], v14 offset:8192
	ds_read_b128 v[208:211], v14 offset:12288
	ds_read_b128 v[240:243], v248 offset:0
	ds_read_b128 v[244:247], v248 offset:4096
	ds_read_b128 v[214:217], v15 offset:0
	ds_read_b128 v[228:231], v15 offset:4096
	ds_read_b128 v[232:235], v15 offset:8192
	ds_read_b128 v[236:239], v15 offset:12288
	s_waitcnt lgkmcnt(4)
	v_mfma_f32_32x32x16_bf16 v[128:143], v[2:5], v[240:243], v[128:143]
	v_mfma_f32_32x32x16_bf16 v[96:111], v[6:9], v[240:243], v[96:111]
	v_mfma_f32_32x32x16_bf16 v[64:79], v[10:13], v[240:243], v[64:79]
	v_mfma_f32_32x32x16_bf16 v[32:47], v[208:211], v[240:243], v[32:47]
	ds_read_b128 v[240:243], v249 offset:0
	v_mfma_f32_32x32x16_bf16 v[112:127], v[2:5], v[244:247], v[112:127]
	v_mfma_f32_32x32x16_bf16 v[80:95], v[6:9], v[244:247], v[80:95]
	v_mfma_f32_32x32x16_bf16 v[48:63], v[10:13], v[244:247], v[48:63]
	v_mfma_f32_32x32x16_bf16 v[16:31], v[208:211], v[244:247], v[16:31]
	ds_read_b128 v[244:247], v249 offset:4096
	ds_read_b128 v[2:5], v205 offset:0
	ds_read_b128 v[6:9], v205 offset:4096
	ds_read_b128 v[10:13], v205 offset:8192
	ds_read_b128 v[208:211], v205 offset:12288
	s_waitcnt lgkmcnt(5)
	v_mfma_f32_32x32x16_bf16 v[128:143], v[214:217], v[240:243], v[128:143]
	v_mfma_f32_32x32x16_bf16 v[96:111], v[228:231], v[240:243], v[96:111]
	v_mfma_f32_32x32x16_bf16 v[64:79], v[232:235], v[240:243], v[64:79]
	v_mfma_f32_32x32x16_bf16 v[32:47], v[236:239], v[240:243], v[32:47]
	ds_read_b128 v[240:243], v250 offset:0
	s_waitcnt lgkmcnt(5)
	v_mfma_f32_32x32x16_bf16 v[112:127], v[214:217], v[244:247], v[112:127]
	v_mfma_f32_32x32x16_bf16 v[80:95], v[228:231], v[244:247], v[80:95]
	v_mfma_f32_32x32x16_bf16 v[48:63], v[232:235], v[244:247], v[48:63]
	v_mfma_f32_32x32x16_bf16 v[16:31], v[236:239], v[244:247], v[16:31]
	ds_read_b128 v[244:247], v250 offset:4096
	ds_read_b128 v[214:217], v0 offset:0
	ds_read_b128 v[228:231], v0 offset:4096
	ds_read_b128 v[232:235], v0 offset:8192
	ds_read_b128 v[236:239], v0 offset:12288
	s_waitcnt lgkmcnt(5)
	v_mfma_f32_32x32x16_bf16 v[128:143], v[2:5], v[240:243], v[128:143]
	v_mfma_f32_32x32x16_bf16 v[96:111], v[6:9], v[240:243], v[96:111]
	v_mfma_f32_32x32x16_bf16 v[64:79], v[10:13], v[240:243], v[64:79]
	v_mfma_f32_32x32x16_bf16 v[32:47], v[208:211], v[240:243], v[32:47]
	ds_read_b128 v[240:243], v251 offset:0
	s_waitcnt lgkmcnt(5)
	v_mfma_f32_32x32x16_bf16 v[112:127], v[2:5], v[244:247], v[112:127]
	v_mfma_f32_32x32x16_bf16 v[80:95], v[6:9], v[244:247], v[80:95]
	v_mfma_f32_32x32x16_bf16 v[48:63], v[10:13], v[244:247], v[48:63]
	v_mfma_f32_32x32x16_bf16 v[16:31], v[208:211], v[244:247], v[16:31]
	ds_read_b128 v[244:247], v251 offset:4096
	s_waitcnt lgkmcnt(1)
	v_mfma_f32_32x32x16_bf16 v[128:143], v[214:217], v[240:243], v[128:143]
	v_mfma_f32_32x32x16_bf16 v[96:111], v[228:231], v[240:243], v[96:111]
	v_mfma_f32_32x32x16_bf16 v[64:79], v[232:235], v[240:243], v[64:79]
	v_mfma_f32_32x32x16_bf16 v[32:47], v[236:239], v[240:243], v[32:47]
	s_waitcnt lgkmcnt(0)
	v_mfma_f32_32x32x16_bf16 v[112:127], v[214:217], v[244:247], v[112:127]
	v_mfma_f32_32x32x16_bf16 v[80:95], v[228:231], v[244:247], v[80:95]
	v_mfma_f32_32x32x16_bf16 v[48:63], v[232:235], v[244:247], v[48:63]
	v_mfma_f32_32x32x16_bf16 v[16:31], v[236:239], v[244:247], v[16:31]
	s_nop 15
	s_nop 7

	s_setprio 0
	s_branch .LBB0_338
